# fixed-reference attention path: exact-zero tile skip distance 127/slope2 (v_exp_f32 returns +0 below 2^-126 on this chip, checked by versions 57/58; running-max path unchanged); output bit-identical
# speedup vs baseline: 1.0172x; 1.0048x over previous
.LBB0_306:
	s_or_b64 exec, exec, s[0:1]
	v_readlane_b32 s0, v252, 1
	v_mov_b32_e32 v169, 0
	v_readlane_b32 s1, v252, 2
	v_mov_b32_e32 v5, 0x8000
	s_waitcnt lgkmcnt(0)
	s_barrier
	v_add_f32_e32 v2, v0, v2
	s_nop 0
	global_load_dword v4, v169, s[0:1] sc1
	v_add_f32_e32 v1, v1, v3
	global_load_dword v5, v5, s[62:63] offset:768 sc1
	s_mov_b32 s0, 0x3fb8aa3b
	v_lshrrev_b32_e32 v7, 4, v209
	v_lshlrev_b32_e32 v10, 4, v209
	v_mul_f32_e32 v13, 0x3fb8aa3b, v2
	v_lshrrev_b32_e32 v8, 5, v209
	v_lshrrev_b32_e32 v9, 3, v209
	v_mul_f32_e32 v14, 0x3fb8aa3b, v1
	v_and_b32_e32 v15, 51, v7
	v_and_b32_e32 v17, 0xf0, v10
	v_mul_u32_u24_e32 v7, 0x1400, v7
	v_fma_f32 v20, v2, s0, -v13
	v_rndne_f32_e32 v21, v13
	v_and_b32_e32 v8, 4, v8
	v_and_b32_e32 v16, 8, v9
	v_fma_f32 v22, v1, s0, -v14
	v_rndne_f32_e32 v23, v14
	v_or_b32_e32 v170, v17, v7
	v_fmac_f32_e32 v20, 0x32a5705f, v2
	v_sub_f32_e32 v7, v13, v21
	v_or3_b32 v8, v15, v8, v16
	v_fmac_f32_e32 v22, 0x32a5705f, v1
	v_sub_f32_e32 v14, v14, v23
	v_add_f32_e32 v7, v7, v20
	v_cvt_i32_f32_e32 v13, v21
	v_mul_u32_u24_e32 v8, 0x110, v8
	v_add_f32_e32 v14, v14, v22
	v_exp_f32_e32 v7, v7
	v_cvt_i32_f32_e32 v15, v23
	v_add3_u32 v212, 0, v8, v17
	v_exp_f32_e32 v8, v14
	s_mov_b32 s1, 0xc2ce8ed0
	v_ldexp_f32 v7, v7, v13
	v_cmp_ngt_f32_e32 vcc, s1, v2
	s_mov_b32 s33, 0x42b17218
	v_ldexp_f32 v8, v8, v15
	v_cndmask_b32_e32 v7, 0, v7, vcc
	v_cmp_ngt_f32_e32 vcc, s1, v1
	v_mov_b32_e32 v3, 0x7f800000
	s_mov_b32 s38, 0xf800000
	v_cndmask_b32_e32 v8, 0, v8, vcc
	v_cmp_nlt_f32_e32 vcc, s33, v2
	s_add_u32 s4, s62, 0xc00000
	s_addc_u32 s5, s63, 0
	v_cndmask_b32_e32 v2, v3, v7, vcc
	v_cmp_nlt_f32_e32 vcc, s33, v1
	s_add_u32 s6, s62, 0xd00000
	s_addc_u32 s7, s63, 0
	v_cndmask_b32_e32 v1, v3, v8, vcc
	v_sub_f32_e32 v1, v2, v1
	v_add_f32_e32 v172, 0x3eb60549, v1
	s_add_u32 s34, s62, 0xe00000
	s_addc_u32 s35, s63, 0
	s_add_u32 s26, s62, 0x1000000
	s_addc_u32 s27, s63, 0
	v_mov_b32_e32 v6, 0x260
	s_add_u32 s24, s62, 0x1b00000
	s_addc_u32 s25, s63, 0
	s_add_u32 s36, s62, 0x1c900000
	s_addc_u32 s37, s63, 0
	v_mul_u32_u24_e32 v11, 0x110, v167
	v_lshlrev_b32_e32 v12, 4, v166
	s_add_u32 s40, s62, 0x8000
	s_addc_u32 s41, s63, 0
	v_add3_u32 v214, 0, v11, v12
	v_lshlrev_b32_e32 v0, 3, v166
	s_add_i32 s66, s64, 0xa00
	v_lshlrev_b32_e32 v168, 2, v167
	v_and_b32_e32 v18, 0x70, v10
	v_mul_u32_u24_e32 v19, 0x10080, v9
	v_mul_u32_u24_e32 v9, 0x90, v9
	v_lshl_add_u64 v[194:195], s[30:31], 0, v[168:169]
	s_movk_i32 s30, 0xff80
	s_mov_b32 s44, 0xfffb0000
	s_movk_i32 s13, 0x1400
	v_mov_b32_e32 v171, v169
	v_lshl_add_u32 v216, v129, 2, 0
	v_lshl_add_u64 v[174:175], s[56:57], 0, v[168:169]
	s_movk_i32 s67, 0x84
	v_or_b32_e32 v219, 8, v177
	s_waitcnt vmcnt(0)
	v_mul_f32_e32 v2, v4, v5
	v_mul_f32_e32 v3, 0x4f800000, v2
	v_cmp_gt_f32_e32 vcc, s38, v2
	v_or_b32_e32 v220, 16, v177
	v_or_b32_e32 v221, 24, v177
	v_cndmask_b32_e32 v2, v2, v3, vcc
	v_sqrt_f32_e32 v3, v2
	v_lshl_add_u64 v[180:181], s[54:55], 0, v[168:169]
	v_lshl_add_u64 v[184:185], s[52:53], 0, v[168:169]
	v_lshl_add_u64 v[186:187], s[48:49], 0, v[168:169]
	v_add_u32_e32 v1, -1, v3
	v_add_u32_e32 v4, 1, v3
	v_fma_f32 v5, -v1, v3, v2
	v_fma_f32 v7, -v4, v3, v2
	v_cmp_ge_f32_e64 s[0:1], 0, v5
	v_mov_b32_e32 v5, v169
	v_lshl_add_u64 v[190:191], s[46:47], 0, v[168:169]
	v_cndmask_b32_e64 v1, v3, v1, s[0:1]
	v_cmp_lt_f32_e64 s[0:1], 0, v7
	v_mov_b32_e32 v173, v172
	v_mov_b32_e32 v165, v166
	v_cndmask_b32_e64 v1, v1, v4, s[0:1]
	v_mul_f32_e32 v3, 0x37800000, v1
	v_cndmask_b32_e32 v1, v1, v3, vcc
	v_cmp_class_f32_e32 vcc, v2, v6
	s_add_i32 s0, 0, 0x12000
	v_add_u32_e32 v217, s0, v12
	v_cndmask_b32_e32 v1, v1, v2, vcc
	v_add_f32_e32 v1, v1, v1
	v_mul_f32_e32 v1, 0x3f828f5c, v1
	v_sub_f32_e32 v253, 0, v1
	v_mov_b32_e32 v254, 0x42400000
	v_cmp_lt_f32_e64 s[98:99], v1, v254
	s_nop 1
	v_cndmask_b32_e64 v253, 0, v253, s[98:99]
	s_getreg_b32 s100, hwreg(HW_REG_XCC_ID, 0, 4)
	s_and_b32 s100, s100, 7
	s_mov_b32 s101, 0
	v_fmaak_f32 v213, 2.0, v1, 0x43160000
	v_mov_b32_e32 v254, 0x42fe0000
	v_cndmask_b32_e64 v213, v213, v254, s[98:99]
	v_lshlrev_b32_e32 v1, 7, v167
	v_sub_u32_e32 v215, v214, v1
	s_mul_i32 s0, s78, 0x2200
	v_and_b32_e32 v1, 56, v200
	s_add_i32 s0, s0, 0
	v_mul_u32_u24_e32 v3, 0x84, v1
	v_lshlrev_b32_e32 v4, 1, v1
	v_lshlrev_b32_e32 v1, 2, v177
	v_add3_u32 v218, s0, v3, v1
	v_add_u32_e32 v1, 0, v10
	v_lshlrev_b32_e32 v2, 2, v166
	s_cmpk_lt_i32 s64, 0x1480
	v_add_u32_e32 v176, s0, v168
	s_mov_b32 s0, 0x20000
	v_add_u32_e32 v224, 0xd000, v1
	v_sub_u32_e32 v1, v167, v0
	s_cselect_b64 s[42:43], -1, 0
	v_lshl_add_u64 v[178:179], s[24:25], 0, v[4:5]
	v_lshl_add_u64 v[182:183], s[26:27], 0, v[4:5]
	v_lshl_add_u64 v[188:189], s[34:35], 0, v[4:5]
	v_lshl_add_u64 v[192:193], s[6:7], 0, v[4:5]
	v_lshl_add_u64 v[196:197], s[4:5], 0, v[4:5]
	v_cmp_gt_i32_e64 s[0:1], s0, v164
	s_lshl_b32 s68, s14, 9
	v_add3_u32 v222, 0, v9, v18
	v_add_u32_e32 v223, 0xfffffe00, v209
	v_or_b32_e32 v198, v19, v18
	v_mov_b32_e32 v199, v169
	v_add_u32_e32 v225, 0xffffff80, v1
	v_lshl_add_u32 v226, s2, 12, v200
	s_lshl_b32 s69, s14, 12
	s_mov_b64 s[52:53], 0
	s_add_i32 s70, 0, 0x12400
	v_lshlrev_b32_e32 v200, 1, v0
	s_movk_i32 s71, 0x27f
	s_mov_b32 s72, 0xc2fc0000
	s_mov_b32 s73, 0xff61b1e6
	s_mov_b32 s74, 0x40c00000
	s_mov_b32 s31, -1
	s_mov_b32 s45, -1
	v_lshlrev_b32_e32 v202, 1, v2
	v_mov_b32_e32 v227, 0x358637bd
	s_movk_i32 s75, 0x2c00
	s_mov_b64 s[46:47], 0x1000
	s_mov_b32 s76, 0x6800000
	s_mov_b32 s77, 0x1a900000
	s_mov_b32 s78, 0x6801000
	s_mov_b32 s79, 0x6802000
	s_mov_b32 s80, 0x6803000
	s_mov_b32 s81, 0x6804000
	s_mov_b64 s[48:49], 0x5000
	s_mov_b32 s82, 0x1ffff
	v_mov_b32_e32 v240, v169
	v_mov_b32_e32 v241, v169
	v_mov_b32_e32 v242, v169
	v_mov_b32_e32 v243, v169
	v_mov_b32_e32 v228, 0x42800000
	v_mov_b32_e32 v229, 0x7149f2ca
	s_branch .LBB0_309
